# baseline (speedup 1.0000x reference)
; __device__ __forceinline__ void gemm_stage(const Params& p, int s, char* smem, const int wv) {
;     ...
;   for (int t = blockIdx.x; t < ntiles; t += gridDim.x) {
;     TileDesc td;
;     td.K = 4096; td.lda = 4096; td.ldb = 4096; td.scale = 1.f; td.aux = nullptr; td.outf = nullptr; td.outb = nullptr; td.ldo = 0; td.outT = nullptr;
;     int pm, pn;
;     if (s == 0) {
;       if (t < 2560) {
;         tile_map(t, 40, 64, pm, pn);
;         td.A = (const u16*)(ws + OFF_WT0I) + (long)pm * 256 * 4096; td.B = H + (long)pn * 256 * 4096;
;         td.mode = pm >= 24 ? EPI_SILU : EPI_PLAIN; td.outb = (u16*)(ws + OFF_PB0); td.ldo = LD0;
;       } else {
;         tile_map(t - 2560, 64, 8, pm, pn);
;         td.A = H + (long)pm * 256 * 4096; td.B = (const u16*)(ws + OFF_WT0I) + (long)(10240 + pn * 256) * 4096;
;         td.mode = EPI_PLAIN; td.outb = (u16*)(ws + OFF_V0T); td.ldo = LDT;
;       }
;       td.brow = pm * 256; td.bcol = pn * 256;
.LBB0_261:
	s_add_i32 s98, s51, s91
	s_cmpk_lt_i32 s98, 0xa00
	s_cbranch_scc0 .Lg0_nopf
	s_lshr_b32 s99, s98, 3
	s_and_b32 s100, s98, 7
	s_lshl_b32 s100, s100, 3
	s_and_b32 s101, s99, 7
	s_or_b32 s100, s100, s101
	s_lshr_b32 s99, s99, 3
	v_readlane_b32 s101, v255, 10
	s_nop 3
	s_lshr_b32 s98, s101, 2
	s_and_b32 s101, s101, 3
	s_lshl_b32 s101, s101, 6
	s_cmp_eq_u32 s98, 0
	s_cbranch_scc0 .Lg0_pfB
	s_lshl_b32 s99, s99, 21
	s_add_u32 s98, s96, s99
	s_addc_u32 s99, s97, 0
	s_branch .Lg0_pfgo
.Lg0_pfB:
	v_readlane_b32 s98, v255, 16
	v_readlane_b32 s99, v255, 17
	s_lshl_b32 s100, s100, 21
	s_nop 3
	s_add_u32 s98, s98, s100
	s_addc_u32 s99, s99, 0
.Lg0_pfgo:
	v_mbcnt_lo_u32_b32 v252, -1, 0
	v_mbcnt_hi_u32_b32 v252, -1, v252
	v_or_b32_e32 v252, s101, v252
	v_lshlrev_b32_e32 v252, 13, v252
	v_mov_b32_e32 v253, 0
	v_lshl_add_u64 v[252:253], s[98:99], 0, v[252:253]
	global_load_dword v254, v[252:253], off offset:128
	global_load_dword v252, v[252:253], off

; __global__ void __launch_bounds__(512) fwd_megakernel(Params p) {
;   extern __shared__ __attribute__((aligned(16))) char smem[];
;   cg::grid_group grid = cg::this_grid();
;   const int wv = __builtin_amdgcn_readfirstlane((int)threadIdx.x >> 6);
;   u32* cnt = (u32*)(p.ws + OFF_CNT);
;   u32 epoch = 0u;
	.amdhsa_kernel _Z14fwd_megakernel6Params
		.amdhsa_group_segment_fixed_size 0
		.amdhsa_private_segment_fixed_size 0
		.amdhsa_kernarg_size 376
		.amdhsa_user_sgpr_count 2
		.amdhsa_user_sgpr_dispatch_ptr 0
		.amdhsa_user_sgpr_queue_ptr 0
		.amdhsa_user_sgpr_kernarg_segment_ptr 1
		.amdhsa_user_sgpr_dispatch_id 0
		.amdhsa_user_sgpr_kernarg_preload_length 0
		.amdhsa_user_sgpr_kernarg_preload_offset 0
		.amdhsa_user_sgpr_private_segment_size 0
		.amdhsa_uses_dynamic_stack 0
		.amdhsa_enable_private_segment 0
		.amdhsa_system_sgpr_workgroup_id_x 1
		.amdhsa_system_sgpr_workgroup_id_y 0
		.amdhsa_system_sgpr_workgroup_id_z 0
		.amdhsa_system_sgpr_workgroup_info 0
		.amdhsa_system_vgpr_workitem_id 2
		.amdhsa_next_free_vgpr 256
		.amdhsa_next_free_sgpr 102
		.amdhsa_accum_offset 256
		.amdhsa_reserve_vcc 1
		.amdhsa_float_round_mode_32 0
		.amdhsa_float_round_mode_16_64 0
		.amdhsa_float_denorm_mode_32 3
		.amdhsa_float_denorm_mode_16_64 3
		.amdhsa_dx10_clamp 1
		.amdhsa_ieee_mode 1
		.amdhsa_fp16_overflow 0
		.amdhsa_tg_split 0
		.amdhsa_exception_fp_ieee_invalid_op 0
		.amdhsa_exception_fp_denorm_src 0
		.amdhsa_exception_fp_ieee_div_zero 0
		.amdhsa_exception_fp_ieee_overflow 0
		.amdhsa_exception_fp_ieee_underflow 0
		.amdhsa_exception_fp_ieee_inexact 0
		.amdhsa_exception_int_div_zero 0
	.end_amdhsa_kernel

; __global__ void __launch_bounds__(512) fwd_megakernel(Params p) {
;   extern __shared__ __attribute__((aligned(16))) char smem[];
;   cg::grid_group grid = cg::this_grid();
;   const int wv = __builtin_amdgcn_readfirstlane((int)threadIdx.x >> 6);
;   u32* cnt = (u32*)(p.ws + OFF_CNT);
;   u32 epoch = 0u;
amdhsa.kernels:
  - .agpr_count:     0
    .args:
      - .offset:         0
        .size:           120
        .value_kind:     by_value
      - .offset:         120
        .size:           4
        .value_kind:     hidden_block_count_x
      - .offset:         124
        .size:           4
        .value_kind:     hidden_block_count_y
      - .offset:         128
        .size:           4
        .value_kind:     hidden_block_count_z
      - .offset:         132
        .size:           2
        .value_kind:     hidden_group_size_x
      - .offset:         134
        .size:           2
        .value_kind:     hidden_group_size_y
      - .offset:         136
        .size:           2
        .value_kind:     hidden_group_size_z
      - .offset:         138
        .size:           2
        .value_kind:     hidden_remainder_x
      - .offset:         140
        .size:           2
        .value_kind:     hidden_remainder_y
      - .offset:         142
        .size:           2
        .value_kind:     hidden_remainder_z
      - .offset:         160
        .size:           8
        .value_kind:     hidden_global_offset_x
      - .offset:         168
        .size:           8
        .value_kind:     hidden_global_offset_y
      - .offset:         176
        .size:           8
        .value_kind:     hidden_global_offset_z
      - .offset:         184
        .size:           2
        .value_kind:     hidden_grid_dims
      - .offset:         208
        .size:           8
        .value_kind:     hidden_multigrid_sync_arg
      - .offset:         240
        .size:           4
        .value_kind:     hidden_dynamic_lds_size
    .group_segment_fixed_size: 0
    .kernarg_segment_align: 8
    .kernarg_segment_size: 376
    .language:       OpenCL C
    .language_version:
      - 2
      - 0
    .max_flat_workgroup_size: 512
    .name:           _Z14fwd_megakernel6Params
    .private_segment_fixed_size: 0
    .sgpr_count:     108
    .sgpr_spill_count: 43
    .symbol:         _Z14fwd_megakernel6Params.kd
    .uniform_work_group_size: 1
    .uses_dynamic_stack: false
    .vgpr_count:     256
    .vgpr_spill_count: 0
    .wavefront_size: 64
